# pipelined attention v5: packed-P converts and l row-sum moved from the softmax block into the next MFMA block PV gaps
# baseline (speedup 1.0000x reference)
; #define MFMA32(a, b, c) __builtin_amdgcn_mfma_f32_32x32x16_bf16((a), (b), (c), 0, 0, 0)
; DI unsigned pk2(float a, float b) { f32x2 v = {a, b}; return __builtin_bit_cast(unsigned, __builtin_convertvector(v, bfv2)); }
; DI void attn_s(const unsigned char* sK, int tt, int qb, int qs, int sub, int l31, int h,
;                const bf16x8 (&qf)[4], f32x16 (&O)[4], float& m, float& l, bf16x8 (&pb)[4]) {
;     ...
;         for (int i = 0; i < 16; ++i) st[k2][i] = __builtin_amdgcn_exp2f(st[k2][i]);
;     {
;         const f32x16 sv = st[0] + st[1];
;         const float ps = (((sv[0] + sv[1]) + (sv[2] + sv[3])) + ((sv[4] + sv[5]) + (sv[6] + sv[7]))) + (((sv[8] + sv[9]) + (sv[10] + sv[11])) + ((sv[12] + sv[13]) + (sv[14] + sv[15])));
;         l += ps;
;     }
; #pragma unroll
;     for (int k4 = 0; k4 < 4; ++k4) {
;         const int k2 = k4 >> 1, o8 = 8 * (k4 & 1);
;         u32x4 pk;
;         pk.x = pk2(st[k2][o8 + 0], st[k2][o8 + 1]); pk.y = pk2(st[k2][o8 + 2], st[k2][o8 + 3]);
;         pk.z = pk2(st[k2][o8 + 4], st[k2][o8 + 5]); pk.w = pk2(st[k2][o8 + 6], st[k2][o8 + 7]);
;         pb[k4] = __builtin_bit_cast(bf16x8, pk);
;     }
; DI void attn_pv(const unsigned char* sV, int l31, int h, const bf16x8 (&pb)[4], f32x16 (&O)[4]) {
;     ...
;         for (int d = 0; d < 4; ++d) O[d] = MFMA32(va[d], pb[0], O[d]);
;         __builtin_amdgcn_sched_barrier(0);
; #pragma unroll
;         for (int d = 0; d < 4; ++d) va[d] = *(const bf16x8*)(vb + d * 32 * A_VROWB + 64);
;         __builtin_amdgcn_sched_barrier(0);
; #pragma unroll
;         for (int d = 0; d < 4; ++d) O[d] = MFMA32(vc[d], pb[1], O[d]);
;         __builtin_amdgcn_sched_barrier(0);
; #pragma unroll
;         for (int d = 0; d < 4; ++d) vc[d] = *(const bf16x8*)(vb + d * 32 * A_VROWB + 96);
;         __builtin_amdgcn_sched_barrier(0);
; #pragma unroll
;         for (int d = 0; d < 4; ++d) O[d] = MFMA32(va[d], pb[2], O[d]);
;         __builtin_amdgcn_sched_barrier(0);
; #pragma unroll
;         for (int d = 0; d < 4; ++d) O[d] = MFMA32(vc[d], pb[3], O[d]);
.Lpipe_norescale_l:
	v_exp_f32_e32 v82, v82
	v_exp_f32_e32 v83, v83
	v_exp_f32_e32 v84, v84
	v_exp_f32_e32 v85, v85
	v_exp_f32_e32 v86, v86
	v_exp_f32_e32 v87, v87
	v_exp_f32_e32 v88, v88
	v_exp_f32_e32 v89, v89
	v_exp_f32_e32 v90, v90
	v_exp_f32_e32 v91, v91
	v_exp_f32_e32 v92, v92
	v_exp_f32_e32 v93, v93
	v_exp_f32_e32 v94, v94
	v_exp_f32_e32 v95, v95
	v_exp_f32_e32 v96, v96
	v_exp_f32_e32 v97, v97
	v_exp_f32_e32 v66, v66
	v_exp_f32_e32 v67, v67
	v_exp_f32_e32 v68, v68
	v_exp_f32_e32 v69, v69
	v_exp_f32_e32 v70, v70
	v_exp_f32_e32 v71, v71
	v_exp_f32_e32 v72, v72
	v_exp_f32_e32 v73, v73
	v_exp_f32_e32 v74, v74
	v_exp_f32_e32 v75, v75
	v_exp_f32_e32 v76, v76
	v_exp_f32_e32 v77, v77
	v_exp_f32_e32 v78, v78
	v_exp_f32_e32 v79, v79
	v_exp_f32_e32 v80, v80
	v_exp_f32_e32 v81, v81
	v_add_u32_e32 v158, 64, v158
	s_mov_b32 s13, s7
	s_add_i32 s4, s7, 1
	s_cmp_lg_u32 s7, 2
	s_cselect_b32 s7, s4, 0
	s_add_i32 s12, s12, 1
	s_cmp_eq_u32 s11, s12
	s_cbranch_scc1 .Lpipe_final
	s_barrier
	s_mul_i32 s98, s13, 0x8c00
	v_add3_u32 v185, s98, v155, v154
	ds_read_b128 v[160:163], v185
	ds_read_b128 v[164:167], v185 offset:32
	ds_read_b128 v[168:171], v185 offset:8704
	ds_read_b128 v[196:199], v185 offset:8736
	v_cvt_pk_bf16_f32 v216, v82, v83
	v_cvt_pk_bf16_f32 v217, v84, v85
	v_cvt_pk_bf16_f32 v218, v86, v87
	v_cvt_pk_bf16_f32 v219, v88, v89
	v_cvt_pk_bf16_f32 v220, v90, v91
	v_cvt_pk_bf16_f32 v221, v92, v93
	s_waitcnt lgkmcnt(11)
	v_mfma_f32_32x32x16_bf16 v[50:65], v[172:175], v[216:219], v[50:65]
	v_cvt_pk_bf16_f32 v222, v94, v95
	v_cvt_pk_bf16_f32 v223, v96, v97
	s_waitcnt lgkmcnt(10)
	v_mfma_f32_32x32x16_bf16 v[34:49], v[176:179], v[216:219], v[34:49]
	v_cvt_pk_bf16_f32 v224, v66, v67
	v_cvt_pk_bf16_f32 v225, v68, v69
	s_waitcnt lgkmcnt(9)
	v_mfma_f32_32x32x16_bf16 v[18:33], v[180:183], v[216:219], v[18:33]
	v_cvt_pk_bf16_f32 v226, v70, v71
	v_cvt_pk_bf16_f32 v227, v72, v73
	s_waitcnt lgkmcnt(8)
	v_mfma_f32_32x32x16_bf16 v[2:17], v[192:195], v[216:219], v[2:17]
	v_cvt_pk_bf16_f32 v228, v74, v75
	v_cvt_pk_bf16_f32 v229, v76, v77
	ds_read_b128 v[172:175], v185 offset:64
	ds_read_b128 v[176:179], v185 offset:96
	ds_read_b128 v[180:183], v185 offset:8768
	ds_read_b128 v[192:195], v185 offset:8800
	v_cvt_pk_bf16_f32 v230, v78, v79
	v_cvt_pk_bf16_f32 v231, v80, v81
	s_waitcnt lgkmcnt(11)
	v_mfma_f32_32x32x16_bf16 v[50:65], v[200:203], v[220:223], v[50:65]
	v_pk_add_f32 v[68:69], v[84:85], v[68:69]
	v_pk_add_f32 v[66:67], v[82:83], v[66:67]
	v_pk_add_f32 v[72:73], v[88:89], v[72:73]
	v_pk_add_f32 v[70:71], v[86:87], v[70:71]
	v_add_f32_e32 v66, v66, v67
	v_add_f32_e32 v67, v68, v69
	s_waitcnt lgkmcnt(10)
	v_mfma_f32_32x32x16_bf16 v[34:49], v[204:207], v[220:223], v[34:49]
	v_add_f32_e32 v66, v66, v67
	v_add_f32_e32 v67, v70, v71
	v_add_f32_e32 v68, v72, v73
	v_pk_add_f32 v[76:77], v[92:93], v[76:77]
	v_pk_add_f32 v[74:75], v[90:91], v[74:75]
	v_add_f32_e32 v67, v67, v68
	s_waitcnt lgkmcnt(9)
	v_mfma_f32_32x32x16_bf16 v[18:33], v[208:211], v[220:223], v[18:33]
	v_pk_add_f32 v[80:81], v[96:97], v[80:81]
	v_pk_add_f32 v[78:79], v[94:95], v[78:79]
	v_add_f32_e32 v66, v66, v67
	v_add_f32_e32 v67, v74, v75
	v_add_f32_e32 v68, v76, v77
	v_add_f32_e32 v67, v67, v68
	s_waitcnt lgkmcnt(8)
	v_mfma_f32_32x32x16_bf16 v[2:17], v[212:215], v[220:223], v[2:17]
	v_add_f32_e32 v68, v78, v79
	v_add_f32_e32 v69, v80, v81
	v_add_f32_e32 v68, v68, v69
	v_add_f32_e32 v67, v67, v68
	v_add_f32_e32 v66, v66, v67
	v_add_f32_e32 v1, v1, v66
	ds_read_b128 v[200:203], v191 offset:17472
	ds_read_b128 v[204:207], v191 offset:22080
	ds_read_b128 v[208:211], v191 offset:26688
	ds_read_b128 v[212:215], v191 offset:31296
	s_waitcnt lgkmcnt(11)
	v_mfma_f32_32x32x16_bf16 v[82:97], v[160:163], v[100:103], v[240:255]
	s_waitcnt lgkmcnt(9)
	v_mfma_f32_32x32x16_bf16 v[66:81], v[168:171], v[100:103], v[240:255]
	v_mfma_f32_32x32x16_bf16 v[82:97], v[164:167], v[104:107], v[82:97]
	s_waitcnt lgkmcnt(8)
	v_mfma_f32_32x32x16_bf16 v[66:81], v[196:199], v[104:107], v[66:81]
	ds_read_b128 v[160:163], v191 offset:17504
	ds_read_b128 v[164:167], v191 offset:22112
	ds_read_b128 v[168:171], v191 offset:26720
	ds_read_b128 v[196:199], v191 offset:31328
	s_waitcnt lgkmcnt(11)
	v_mfma_f32_32x32x16_bf16 v[82:97], v[172:175], v[108:111], v[82:97]
	s_waitcnt lgkmcnt(9)
	v_mfma_f32_32x32x16_bf16 v[66:81], v[180:183], v[108:111], v[66:81]
	v_mfma_f32_32x32x16_bf16 v[82:97], v[176:179], v[112:115], v[82:97]
	s_waitcnt lgkmcnt(8)
	v_mfma_f32_32x32x16_bf16 v[66:81], v[192:195], v[112:115], v[66:81]
	s_add_i32 s14, s12, 0x42
	s_cmp_ge_i32 s14, s6
	s_cbranch_scc1 .Lpipe_nost_l
	s_mul_i32 s4, s7, 0x8c00
	s_add_i32 s4, s4, 0
	v_add_u32_e32 v184, s4, v140
	v_add_u32_e32 v185, v184, v139
	v_add_u32_e32 v184, v184, v141
	s_waitcnt vmcnt(3)
	ds_write_b128 v185, v[116:119]
	s_waitcnt vmcnt(2)
	ds_write_b128 v184, v[120:123]
	v_add3_u32 v184, s4, v150, v151
	v_add_u32_e32 v185, v184, v152
	v_add_u32_e32 v184, v184, v153
	v_add_u32_e32 v185, 0x4000, v185
	v_add_u32_e32 v184, 0x4000, v184
	s_waitcnt vmcnt(1)
	ds_write2_b64 v185, v[124:125], v[126:127] offset0:128 offset1:130
	s_waitcnt vmcnt(0)
	ds_write2_b64 v184, v[128:129], v[130:131] offset0:128 offset1:130

; #define MFMA32(a, b, c) __builtin_amdgcn_mfma_f32_32x32x16_bf16((a), (b), (c), 0, 0, 0)
; DI unsigned pk2(float a, float b) { f32x2 v = {a, b}; return __builtin_bit_cast(unsigned, __builtin_convertvector(v, bfv2)); }
; DI void attn_s(const unsigned char* sK, int tt, int qb, int qs, int sub, int l31, int h,
;                const bf16x8 (&qf)[4], f32x16 (&O)[4], float& m, float& l, bf16x8 (&pb)[4]) {
;     ...
;         for (int i = 0; i < 16; ++i) st[k2][i] = __builtin_amdgcn_exp2f(st[k2][i]);
;     {
;         const f32x16 sv = st[0] + st[1];
;         const float ps = (((sv[0] + sv[1]) + (sv[2] + sv[3])) + ((sv[4] + sv[5]) + (sv[6] + sv[7]))) + (((sv[8] + sv[9]) + (sv[10] + sv[11])) + ((sv[12] + sv[13]) + (sv[14] + sv[15])));
;         l += ps;
;     }
; #pragma unroll
;     for (int k4 = 0; k4 < 4; ++k4) {
;         const int k2 = k4 >> 1, o8 = 8 * (k4 & 1);
;         u32x4 pk;
;         pk.x = pk2(st[k2][o8 + 0], st[k2][o8 + 1]); pk.y = pk2(st[k2][o8 + 2], st[k2][o8 + 3]);
;         pk.z = pk2(st[k2][o8 + 4], st[k2][o8 + 5]); pk.w = pk2(st[k2][o8 + 6], st[k2][o8 + 7]);
;         pb[k4] = __builtin_bit_cast(bf16x8, pk);
;     }
; DI void attn_pv(const unsigned char* sV, int l31, int h, const bf16x8 (&pb)[4], f32x16 (&O)[4]) {
;     ...
;         for (int d = 0; d < 4; ++d) O[d] = MFMA32(va[d], pb[0], O[d]);
;         __builtin_amdgcn_sched_barrier(0);
; #pragma unroll
;         for (int d = 0; d < 4; ++d) va[d] = *(const bf16x8*)(vb + d * 32 * A_VROWB + 64);
;         __builtin_amdgcn_sched_barrier(0);
; #pragma unroll
;         for (int d = 0; d < 4; ++d) O[d] = MFMA32(vc[d], pb[1], O[d]);
;         __builtin_amdgcn_sched_barrier(0);
; #pragma unroll
;         for (int d = 0; d < 4; ++d) vc[d] = *(const bf16x8*)(vb + d * 32 * A_VROWB + 96);
;         __builtin_amdgcn_sched_barrier(0);
; #pragma unroll
;         for (int d = 0; d < 4; ++d) O[d] = MFMA32(va[d], pb[2], O[d]);
;         __builtin_amdgcn_sched_barrier(0);
; #pragma unroll
;         for (int d = 0; d < 4; ++d) O[d] = MFMA32(vc[d], pb[3], O[d]);
.Lpipe_final:
	s_barrier
	v_cvt_pk_bf16_f32 v216, v82, v83
	v_cvt_pk_bf16_f32 v217, v84, v85
	v_cvt_pk_bf16_f32 v218, v86, v87
	v_cvt_pk_bf16_f32 v219, v88, v89
	v_cvt_pk_bf16_f32 v220, v90, v91
	v_cvt_pk_bf16_f32 v221, v92, v93
	v_cvt_pk_bf16_f32 v222, v94, v95
	v_cvt_pk_bf16_f32 v223, v96, v97
	v_cvt_pk_bf16_f32 v224, v66, v67
	v_cvt_pk_bf16_f32 v225, v68, v69
	v_cvt_pk_bf16_f32 v226, v70, v71
	v_cvt_pk_bf16_f32 v227, v72, v73
	v_cvt_pk_bf16_f32 v228, v74, v75
	v_cvt_pk_bf16_f32 v229, v76, v77
	v_cvt_pk_bf16_f32 v230, v78, v79
	v_cvt_pk_bf16_f32 v231, v80, v81
	s_waitcnt lgkmcnt(7)
	v_mfma_f32_32x32x16_bf16 v[50:65], v[172:175], v[216:219], v[50:65]
	s_waitcnt lgkmcnt(6)
	v_mfma_f32_32x32x16_bf16 v[34:49], v[176:179], v[216:219], v[34:49]
	s_waitcnt lgkmcnt(5)
	v_mfma_f32_32x32x16_bf16 v[18:33], v[180:183], v[216:219], v[18:33]
	s_waitcnt lgkmcnt(4)
	v_mfma_f32_32x32x16_bf16 v[2:17], v[192:195], v[216:219], v[2:17]
	ds_read_b128 v[160:163], v191 offset:17472
	ds_read_b128 v[164:167], v191 offset:22080
	ds_read_b128 v[168:171], v191 offset:26688
	ds_read_b128 v[196:199], v191 offset:31296
	ds_read_b128 v[172:175], v191 offset:17504
	ds_read_b128 v[176:179], v191 offset:22112
	ds_read_b128 v[180:183], v191 offset:26720
	ds_read_b128 v[192:195], v191 offset:31328
	s_waitcnt lgkmcnt(11)
	v_mfma_f32_32x32x16_bf16 v[50:65], v[200:203], v[220:223], v[50:65]
	v_pk_add_f32 v[68:69], v[84:85], v[68:69]
	v_pk_add_f32 v[66:67], v[82:83], v[66:67]
	v_pk_add_f32 v[72:73], v[88:89], v[72:73]
	v_pk_add_f32 v[70:71], v[86:87], v[70:71]
	v_add_f32_e32 v66, v66, v67
	v_add_f32_e32 v67, v68, v69
	s_waitcnt lgkmcnt(10)
	v_mfma_f32_32x32x16_bf16 v[34:49], v[204:207], v[220:223], v[34:49]
	v_add_f32_e32 v66, v66, v67
	v_add_f32_e32 v67, v70, v71
	v_add_f32_e32 v68, v72, v73
	v_pk_add_f32 v[76:77], v[92:93], v[76:77]
	v_pk_add_f32 v[74:75], v[90:91], v[74:75]
	v_add_f32_e32 v67, v67, v68
	s_waitcnt lgkmcnt(9)
	v_mfma_f32_32x32x16_bf16 v[18:33], v[208:211], v[220:223], v[18:33]
	v_pk_add_f32 v[80:81], v[96:97], v[80:81]
	v_pk_add_f32 v[78:79], v[94:95], v[78:79]
	v_add_f32_e32 v66, v66, v67
	v_add_f32_e32 v67, v74, v75
	v_add_f32_e32 v68, v76, v77
	v_add_f32_e32 v67, v67, v68
	s_waitcnt lgkmcnt(8)
	v_mfma_f32_32x32x16_bf16 v[2:17], v[212:215], v[220:223], v[2:17]
	v_add_f32_e32 v68, v78, v79
	v_add_f32_e32 v69, v80, v81
	v_add_f32_e32 v68, v68, v69
	v_add_f32_e32 v67, v67, v68
	v_add_f32_e32 v66, v66, v67
	v_add_f32_e32 v1, v1, v66
	s_waitcnt lgkmcnt(7)
	v_mfma_f32_32x32x16_bf16 v[50:65], v[160:163], v[224:227], v[50:65]
	s_waitcnt lgkmcnt(6)
	v_mfma_f32_32x32x16_bf16 v[34:49], v[164:167], v[224:227], v[34:49]
	s_waitcnt lgkmcnt(5)
	v_mfma_f32_32x32x16_bf16 v[18:33], v[168:171], v[224:227], v[18:33]
	s_waitcnt lgkmcnt(4)
	v_mfma_f32_32x32x16_bf16 v[2:17], v[196:199], v[224:227], v[2:17]
	s_waitcnt lgkmcnt(3)
	v_mfma_f32_32x32x16_bf16 v[50:65], v[172:175], v[228:231], v[50:65]
	s_waitcnt lgkmcnt(2)
	v_mfma_f32_32x32x16_bf16 v[34:49], v[176:179], v[228:231], v[34:49]
	s_waitcnt lgkmcnt(1)
	v_mfma_f32_32x32x16_bf16 v[18:33], v[180:183], v[228:231], v[18:33]
	s_waitcnt lgkmcnt(0)
	v_mfma_f32_32x32x16_bf16 v[2:17], v[192:195], v[228:231], v[2:17]
	s_barrier
	s_cmp_eq_u32 s99, 1
	s_cbranch_scc1 .Lpipe_done
	s_barrier
